# v38 + MLA loop v5: v4 (sum-based overflow check, no row-max tree) with the first key-half exps and sums interleaved under the QK2 MFMAs
# speedup vs baseline: 1.0125x; 1.0093x over previous
.Lm_noload:
	s_cmp_gt_i32 s20, s35
	s_cbranch_scc1 .LBB0_379
	s_bitcmp1_b32 s20, 0
	s_cselect_b32 s38, 0xb400, 0
	v_add_u32_e32 v8, s38, v191
	ds_read_b128 v[10:13], v8
	ds_read_b128 v[14:17], v8 offset:32
	ds_read_b128 v[202:205], v8 offset:64
	ds_read_b128 v[206:209], v8 offset:96
	v_add_u32_e32 v197, s38, v196
	s_setprio 3
	s_waitcnt lgkmcnt(3)
	v_mfma_f32_32x32x16_bf16 v[100:115], v[10:13], v[116:119], v[210:225]
	ds_read_b128 v[10:13], v8 offset:128
	s_waitcnt lgkmcnt(3)
	v_mfma_f32_32x32x16_bf16 v[100:115], v[14:17], v[120:123], v[100:115]
	ds_read_b128 v[14:17], v8 offset:160
	s_waitcnt lgkmcnt(3)
	v_mfma_f32_32x32x16_bf16 v[100:115], v[202:205], v[124:127], v[100:115]
	ds_read_b128 v[202:205], v8 offset:192
	s_waitcnt lgkmcnt(3)
	v_mfma_f32_32x32x16_bf16 v[100:115], v[206:209], v[132:135], v[100:115]
	ds_read_b128 v[206:209], v8 offset:224
	s_waitcnt lgkmcnt(3)
	v_mfma_f32_32x32x16_bf16 v[100:115], v[10:13], v[136:139], v[100:115]
	ds_read_b128 v[10:13], v8 offset:256
	s_waitcnt lgkmcnt(3)
	v_mfma_f32_32x32x16_bf16 v[100:115], v[14:17], v[140:143], v[100:115]
	ds_read_b128 v[14:17], v8 offset:288
	s_waitcnt lgkmcnt(3)
	v_mfma_f32_32x32x16_bf16 v[100:115], v[202:205], v[144:147], v[100:115]
	ds_read_b128 v[202:205], v8 offset:320
	s_waitcnt lgkmcnt(3)
	v_mfma_f32_32x32x16_bf16 v[100:115], v[206:209], v[148:151], v[100:115]
	ds_read_b128 v[206:209], v8 offset:352
	s_waitcnt lgkmcnt(3)
	v_mfma_f32_32x32x16_bf16 v[100:115], v[10:13], v[152:155], v[100:115]
	ds_read_b128 v[10:13], v8 offset:12800
	s_waitcnt lgkmcnt(3)
	v_mfma_f32_32x32x16_bf16 v[100:115], v[14:17], v[156:159], v[100:115]
	ds_read_b128 v[14:17], v8 offset:12832
	s_waitcnt lgkmcnt(3)
	v_mfma_f32_32x32x16_bf16 v[100:115], v[202:205], v[160:163], v[100:115]
	ds_read_b128 v[202:205], v8 offset:12864
	s_waitcnt lgkmcnt(3)
	v_mfma_f32_32x32x16_bf16 v[100:115], v[206:209], v[164:167], v[100:115]
	ds_read_b128 v[206:209], v8 offset:12896
	s_waitcnt lgkmcnt(3)
	v_mfma_f32_32x32x16_bf16 v[84:99], v[10:13], v[116:119], v[210:225]
	ds_read_b128 v[10:13], v8 offset:12928
	s_waitcnt lgkmcnt(3)
	v_mfma_f32_32x32x16_bf16 v[84:99], v[14:17], v[120:123], v[84:99]
	ds_read_b128 v[14:17], v8 offset:12960
	s_waitcnt lgkmcnt(3)
	v_mfma_f32_32x32x16_bf16 v[84:99], v[202:205], v[124:127], v[84:99]
	ds_read_b128 v[202:205], v8 offset:12992
	s_waitcnt lgkmcnt(3)
	v_mfma_f32_32x32x16_bf16 v[84:99], v[206:209], v[132:135], v[84:99]
	ds_read_b128 v[206:209], v8 offset:13024
	s_waitcnt lgkmcnt(3)
	v_mfma_f32_32x32x16_bf16 v[84:99], v[10:13], v[136:139], v[84:99]
	ds_read_b128 v[10:13], v8 offset:13056
	v_exp_f32_e32 v100, v100
	v_exp_f32_e32 v101, v101
	s_waitcnt lgkmcnt(3)
	v_mfma_f32_32x32x16_bf16 v[84:99], v[14:17], v[140:143], v[84:99]
	ds_read_b128 v[14:17], v8 offset:13088
	v_exp_f32_e32 v102, v102
	v_exp_f32_e32 v103, v103
	v_add_f32_e32 v234, 0, v100
	v_add_f32_e32 v234, v101, v234
	s_waitcnt lgkmcnt(3)
	v_mfma_f32_32x32x16_bf16 v[84:99], v[202:205], v[144:147], v[84:99]
	ds_read_b128 v[202:205], v8 offset:13120
	v_exp_f32_e32 v104, v104
	v_exp_f32_e32 v105, v105
	v_add_f32_e32 v234, v102, v234
	v_add_f32_e32 v234, v103, v234
	s_waitcnt lgkmcnt(3)
	v_mfma_f32_32x32x16_bf16 v[84:99], v[206:209], v[148:151], v[84:99]
	ds_read_b128 v[206:209], v8 offset:13152
	v_exp_f32_e32 v106, v106
	v_exp_f32_e32 v107, v107
	v_add_f32_e32 v234, v104, v234
	v_add_f32_e32 v234, v105, v234
	s_waitcnt lgkmcnt(3)
	v_mfma_f32_32x32x16_bf16 v[84:99], v[10:13], v[152:155], v[84:99]
	ds_read_b64_tr_b16 v[10:11], v197 offset:25600
	ds_read_b64_tr_b16 v[12:13], v197 offset:28160
	v_exp_f32_e32 v108, v108
	v_exp_f32_e32 v109, v109
	v_add_f32_e32 v234, v106, v234
	v_add_f32_e32 v234, v107, v234
	s_waitcnt lgkmcnt(4)
	v_mfma_f32_32x32x16_bf16 v[84:99], v[14:17], v[156:159], v[84:99]
	ds_read_b64_tr_b16 v[14:15], v197 offset:25664
	ds_read_b64_tr_b16 v[16:17], v197 offset:28224
	v_exp_f32_e32 v110, v110
	v_exp_f32_e32 v111, v111
	v_add_f32_e32 v234, v108, v234
	v_add_f32_e32 v234, v109, v234
	s_waitcnt lgkmcnt(5)
	v_mfma_f32_32x32x16_bf16 v[84:99], v[202:205], v[160:163], v[84:99]
	ds_read_b64_tr_b16 v[202:203], v197 offset:25728
	ds_read_b64_tr_b16 v[204:205], v197 offset:28288
	v_exp_f32_e32 v112, v112
	v_exp_f32_e32 v113, v113
	v_add_f32_e32 v234, v110, v234
	v_add_f32_e32 v234, v111, v234
	s_waitcnt lgkmcnt(6)
	v_mfma_f32_32x32x16_bf16 v[84:99], v[206:209], v[164:167], v[84:99]
	ds_read_b64_tr_b16 v[206:207], v197 offset:25792
	ds_read_b64_tr_b16 v[208:209], v197 offset:28352
	v_exp_f32_e32 v114, v114
	v_exp_f32_e32 v115, v115
	v_add_f32_e32 v234, v112, v234
	v_add_f32_e32 v234, v113, v234
	v_add_f32_e32 v234, v114, v234
	v_add_f32_e32 v234, v115, v234
	s_and_b64 vcc, exec, s[18:19]
	s_cbranch_vccz .Lm_p1
	s_setprio 0
	s_branch .Lm_pd

.Lm_pd:
	s_nop 3
	v_exp_f32_e32 v84, v84
	v_exp_f32_e32 v85, v85
	v_exp_f32_e32 v86, v86
	v_exp_f32_e32 v87, v87
	v_exp_f32_e32 v88, v88
	v_exp_f32_e32 v89, v89
	v_exp_f32_e32 v90, v90
	v_exp_f32_e32 v91, v91
	v_exp_f32_e32 v92, v92
	v_exp_f32_e32 v93, v93
	v_exp_f32_e32 v94, v94
	v_exp_f32_e32 v95, v95
	v_exp_f32_e32 v96, v96
	v_exp_f32_e32 v97, v97
	v_exp_f32_e32 v98, v98
	v_exp_f32_e32 v99, v99
	v_add_f32_e32 v234, v84, v234
	v_add_f32_e32 v234, v85, v234
	v_add_f32_e32 v234, v86, v234
	v_add_f32_e32 v234, v87, v234
	v_add_f32_e32 v234, v88, v234
	v_add_f32_e32 v234, v89, v234
	v_add_f32_e32 v234, v90, v234
	v_add_f32_e32 v234, v91, v234
	v_add_f32_e32 v234, v92, v234
	v_add_f32_e32 v234, v93, v234
	v_add_f32_e32 v234, v94, v234
	v_add_f32_e32 v234, v95, v234
	v_add_f32_e32 v234, v96, v234
	v_add_f32_e32 v234, v97, v234
	v_add_f32_e32 v234, v98, v234
	v_add_f32_e32 v234, v99, v234
	v_cmp_lt_f32_e32 vcc, 0x47800000, v234
	s_cbranch_vccnz .Lm_R
.Lm_post:
	v_add_f32_e32 v193, v193, v234
	v_cvt_pk_bf16_f32 v226, v100, v101
	v_cvt_pk_bf16_f32 v227, v102, v103
	v_cvt_pk_bf16_f32 v228, v104, v105
	v_cvt_pk_bf16_f32 v229, v106, v107
	v_cvt_pk_bf16_f32 v230, v108, v109
	v_cvt_pk_bf16_f32 v231, v110, v111
	v_cvt_pk_bf16_f32 v232, v112, v113
	v_cvt_pk_bf16_f32 v233, v114, v115
	ds_read_b64_tr_b16 v[100:101], v197 offset:30720
	ds_read_b64_tr_b16 v[102:103], v197 offset:33280
	ds_read_b64_tr_b16 v[104:105], v197 offset:30784
	ds_read_b64_tr_b16 v[106:107], v197 offset:33344
	ds_read_b64_tr_b16 v[108:109], v197 offset:30848
	ds_read_b64_tr_b16 v[110:111], v197 offset:33408
	ds_read_b64_tr_b16 v[112:113], v197 offset:30912
	ds_read_b64_tr_b16 v[114:115], v197 offset:33472
	s_waitcnt lgkmcnt(14)
	v_mfma_f32_32x32x16_bf16 v[68:83], v[10:13], v[226:229], v[68:83]
	s_waitcnt lgkmcnt(12)
	v_mfma_f32_32x32x16_bf16 v[52:67], v[14:17], v[226:229], v[52:67]
	s_waitcnt lgkmcnt(10)
	v_mfma_f32_32x32x16_bf16 v[36:51], v[202:205], v[226:229], v[36:51]
	s_waitcnt lgkmcnt(8)
	v_mfma_f32_32x32x16_bf16 v[20:35], v[206:209], v[226:229], v[20:35]
	ds_read_b64_tr_b16 v[10:11], v197 offset:35840
	ds_read_b64_tr_b16 v[12:13], v197 offset:38400
	ds_read_b64_tr_b16 v[14:15], v197 offset:35904
	ds_read_b64_tr_b16 v[16:17], v197 offset:38464
	ds_read_b64_tr_b16 v[202:203], v197 offset:35968
	ds_read_b64_tr_b16 v[204:205], v197 offset:38528
	ds_read_b64_tr_b16 v[206:207], v197 offset:36032
	ds_read_b64_tr_b16 v[208:209], v197 offset:38592
	v_cvt_pk_bf16_f32 v226, v84, v85
	v_cvt_pk_bf16_f32 v227, v86, v87
	v_cvt_pk_bf16_f32 v228, v88, v89
	v_cvt_pk_bf16_f32 v229, v90, v91
	s_waitcnt lgkmcnt(14)
	v_mfma_f32_32x32x16_bf16 v[68:83], v[100:103], v[230:233], v[68:83]
	s_waitcnt lgkmcnt(12)
	v_mfma_f32_32x32x16_bf16 v[52:67], v[104:107], v[230:233], v[52:67]
	s_waitcnt lgkmcnt(10)
	v_mfma_f32_32x32x16_bf16 v[36:51], v[108:111], v[230:233], v[36:51]
	s_waitcnt lgkmcnt(8)
	v_mfma_f32_32x32x16_bf16 v[20:35], v[112:115], v[230:233], v[20:35]
	ds_read_b64_tr_b16 v[100:101], v197 offset:40960
	ds_read_b64_tr_b16 v[102:103], v197 offset:43520
	ds_read_b64_tr_b16 v[104:105], v197 offset:41024
	ds_read_b64_tr_b16 v[106:107], v197 offset:43584
	ds_read_b64_tr_b16 v[108:109], v197 offset:41088
	ds_read_b64_tr_b16 v[110:111], v197 offset:43648
	ds_read_b64_tr_b16 v[112:113], v197 offset:41152
	ds_read_b64_tr_b16 v[114:115], v197 offset:43712
	v_cvt_pk_bf16_f32 v230, v92, v93
	v_cvt_pk_bf16_f32 v231, v94, v95
	v_cvt_pk_bf16_f32 v232, v96, v97
	v_cvt_pk_bf16_f32 v233, v98, v99
	s_waitcnt lgkmcnt(14)
	v_mfma_f32_32x32x16_bf16 v[68:83], v[10:13], v[226:229], v[68:83]
	s_waitcnt lgkmcnt(12)
	v_mfma_f32_32x32x16_bf16 v[52:67], v[14:17], v[226:229], v[52:67]
	s_waitcnt lgkmcnt(10)
	v_mfma_f32_32x32x16_bf16 v[36:51], v[202:205], v[226:229], v[36:51]
	s_waitcnt lgkmcnt(8)
	v_mfma_f32_32x32x16_bf16 v[20:35], v[206:209], v[226:229], v[20:35]
	s_waitcnt lgkmcnt(6)
	v_mfma_f32_32x32x16_bf16 v[68:83], v[100:103], v[230:233], v[68:83]
	s_waitcnt lgkmcnt(4)
	v_mfma_f32_32x32x16_bf16 v[52:67], v[104:107], v[230:233], v[52:67]
	s_waitcnt lgkmcnt(2)
	v_mfma_f32_32x32x16_bf16 v[36:51], v[108:111], v[230:233], v[36:51]
	s_waitcnt lgkmcnt(0)
	v_mfma_f32_32x32x16_bf16 v[20:35], v[112:115], v[230:233], v[20:35]

.Lm_R:
	s_waitcnt lgkmcnt(0)
	ds_read_b128 v[10:13], v8
	ds_read_b128 v[14:17], v8 offset:32
	ds_read_b128 v[202:205], v8 offset:64
	ds_read_b128 v[206:209], v8 offset:96
	s_waitcnt lgkmcnt(3)
	v_mfma_f32_32x32x16_bf16 v[100:115], v[10:13], v[116:119], v[210:225]
	ds_read_b128 v[10:13], v8 offset:128
	s_waitcnt lgkmcnt(3)
	v_mfma_f32_32x32x16_bf16 v[100:115], v[14:17], v[120:123], v[100:115]
	ds_read_b128 v[14:17], v8 offset:160
	s_waitcnt lgkmcnt(3)
	v_mfma_f32_32x32x16_bf16 v[100:115], v[202:205], v[124:127], v[100:115]
	ds_read_b128 v[202:205], v8 offset:192
	s_waitcnt lgkmcnt(3)
	v_mfma_f32_32x32x16_bf16 v[100:115], v[206:209], v[132:135], v[100:115]
	ds_read_b128 v[206:209], v8 offset:224
	s_waitcnt lgkmcnt(3)
	v_mfma_f32_32x32x16_bf16 v[100:115], v[10:13], v[136:139], v[100:115]
	ds_read_b128 v[10:13], v8 offset:256
	s_waitcnt lgkmcnt(3)
	v_mfma_f32_32x32x16_bf16 v[100:115], v[14:17], v[140:143], v[100:115]
	ds_read_b128 v[14:17], v8 offset:288
	s_waitcnt lgkmcnt(3)
	v_mfma_f32_32x32x16_bf16 v[100:115], v[202:205], v[144:147], v[100:115]
	ds_read_b128 v[202:205], v8 offset:320
	s_waitcnt lgkmcnt(3)
	v_mfma_f32_32x32x16_bf16 v[100:115], v[206:209], v[148:151], v[100:115]
	ds_read_b128 v[206:209], v8 offset:352
	s_waitcnt lgkmcnt(3)
	v_mfma_f32_32x32x16_bf16 v[100:115], v[10:13], v[152:155], v[100:115]
	ds_read_b128 v[10:13], v8 offset:12800
	s_waitcnt lgkmcnt(3)
	v_mfma_f32_32x32x16_bf16 v[100:115], v[14:17], v[156:159], v[100:115]
	ds_read_b128 v[14:17], v8 offset:12832
	s_waitcnt lgkmcnt(3)
	v_mfma_f32_32x32x16_bf16 v[100:115], v[202:205], v[160:163], v[100:115]
	ds_read_b128 v[202:205], v8 offset:12864
	s_waitcnt lgkmcnt(3)
	v_mfma_f32_32x32x16_bf16 v[100:115], v[206:209], v[164:167], v[100:115]
	ds_read_b128 v[206:209], v8 offset:12896
	s_waitcnt lgkmcnt(3)
	v_mfma_f32_32x32x16_bf16 v[84:99], v[10:13], v[116:119], v[210:225]
	ds_read_b128 v[10:13], v8 offset:12928
	s_waitcnt lgkmcnt(3)
	v_mfma_f32_32x32x16_bf16 v[84:99], v[14:17], v[120:123], v[84:99]
	ds_read_b128 v[14:17], v8 offset:12960
	s_waitcnt lgkmcnt(3)
	v_mfma_f32_32x32x16_bf16 v[84:99], v[202:205], v[124:127], v[84:99]
	ds_read_b128 v[202:205], v8 offset:12992
	s_waitcnt lgkmcnt(3)
	v_mfma_f32_32x32x16_bf16 v[84:99], v[206:209], v[132:135], v[84:99]
	ds_read_b128 v[206:209], v8 offset:13024
	s_waitcnt lgkmcnt(3)
	v_mfma_f32_32x32x16_bf16 v[84:99], v[10:13], v[136:139], v[84:99]
	ds_read_b128 v[10:13], v8 offset:13056
	s_waitcnt lgkmcnt(3)
	v_mfma_f32_32x32x16_bf16 v[84:99], v[14:17], v[140:143], v[84:99]
	ds_read_b128 v[14:17], v8 offset:13088
	s_waitcnt lgkmcnt(3)
	v_mfma_f32_32x32x16_bf16 v[84:99], v[202:205], v[144:147], v[84:99]
	ds_read_b128 v[202:205], v8 offset:13120
	s_waitcnt lgkmcnt(3)
	v_mfma_f32_32x32x16_bf16 v[84:99], v[206:209], v[148:151], v[84:99]
	ds_read_b128 v[206:209], v8 offset:13152
	s_waitcnt lgkmcnt(3)
	v_mfma_f32_32x32x16_bf16 v[84:99], v[10:13], v[152:155], v[84:99]
	s_waitcnt lgkmcnt(2)
	v_mfma_f32_32x32x16_bf16 v[84:99], v[14:17], v[156:159], v[84:99]
	s_waitcnt lgkmcnt(1)
	v_mfma_f32_32x32x16_bf16 v[84:99], v[202:205], v[160:163], v[84:99]
	s_waitcnt lgkmcnt(0)
	v_mfma_f32_32x32x16_bf16 v[84:99], v[206:209], v[164:167], v[84:99]
	v_max3_f32 v235, v100, v101, v102
	v_max3_f32 v235, v235, v103, v104
	v_max3_f32 v235, v235, v105, v106
	v_max3_f32 v235, v235, v107, v108
	v_max3_f32 v235, v235, v109, v110
	v_max3_f32 v235, v235, v111, v112
	v_max3_f32 v235, v235, v113, v114
	s_nop 4
	v_max3_f32 v235, v235, v115, v84
	v_max3_f32 v235, v235, v85, v86
	v_max3_f32 v235, v235, v87, v88
	v_max3_f32 v235, v235, v89, v90
	v_max3_f32 v235, v235, v91, v92
	v_max3_f32 v235, v235, v93, v94
	v_max3_f32 v235, v235, v95, v96
	v_max3_f32 v235, v235, v97, v98
	v_max3_f32 v235, v235, v99, v99
	v_mov_b32_e32 v237, v235
	v_mov_b32_e32 v239, v235
	s_nop 1
	v_permlane32_swap_b32_e32 v237, v239
	v_cndmask_b32_e64 v237, v237, v239, s[4:5]
	v_max_f32_e32 v237, v237, v237
	v_max_f32_e32 v236, v235, v237
	v_max_f32_e32 v236, 0, v236
	v_exp_f32_e64 v238, -v236
	v_pk_add_f32 v[100:101], v[100:101], v[236:237] op_sel_hi:[1,0] neg_lo:[0,1] neg_hi:[0,1]
	v_pk_add_f32 v[102:103], v[102:103], v[236:237] op_sel_hi:[1,0] neg_lo:[0,1] neg_hi:[0,1]
	v_pk_add_f32 v[104:105], v[104:105], v[236:237] op_sel_hi:[1,0] neg_lo:[0,1] neg_hi:[0,1]
	v_pk_add_f32 v[106:107], v[106:107], v[236:237] op_sel_hi:[1,0] neg_lo:[0,1] neg_hi:[0,1]
	v_pk_add_f32 v[108:109], v[108:109], v[236:237] op_sel_hi:[1,0] neg_lo:[0,1] neg_hi:[0,1]
	v_pk_add_f32 v[110:111], v[110:111], v[236:237] op_sel_hi:[1,0] neg_lo:[0,1] neg_hi:[0,1]
	v_pk_add_f32 v[112:113], v[112:113], v[236:237] op_sel_hi:[1,0] neg_lo:[0,1] neg_hi:[0,1]
	v_pk_add_f32 v[114:115], v[114:115], v[236:237] op_sel_hi:[1,0] neg_lo:[0,1] neg_hi:[0,1]
	v_pk_add_f32 v[84:85], v[84:85], v[236:237] op_sel_hi:[1,0] neg_lo:[0,1] neg_hi:[0,1]
	v_pk_add_f32 v[86:87], v[86:87], v[236:237] op_sel_hi:[1,0] neg_lo:[0,1] neg_hi:[0,1]
	v_pk_add_f32 v[88:89], v[88:89], v[236:237] op_sel_hi:[1,0] neg_lo:[0,1] neg_hi:[0,1]
	v_pk_add_f32 v[90:91], v[90:91], v[236:237] op_sel_hi:[1,0] neg_lo:[0,1] neg_hi:[0,1]
	v_pk_add_f32 v[92:93], v[92:93], v[236:237] op_sel_hi:[1,0] neg_lo:[0,1] neg_hi:[0,1]
	v_pk_add_f32 v[94:95], v[94:95], v[236:237] op_sel_hi:[1,0] neg_lo:[0,1] neg_hi:[0,1]
	v_pk_add_f32 v[96:97], v[96:97], v[236:237] op_sel_hi:[1,0] neg_lo:[0,1] neg_hi:[0,1]
	v_pk_add_f32 v[98:99], v[98:99], v[236:237] op_sel_hi:[1,0] neg_lo:[0,1] neg_hi:[0,1]
	v_pk_add_f32 v[210:211], v[210:211], v[236:237] op_sel_hi:[1,0] neg_lo:[0,1] neg_hi:[0,1]
	v_pk_add_f32 v[212:213], v[212:213], v[236:237] op_sel_hi:[1,0] neg_lo:[0,1] neg_hi:[0,1]
	v_pk_add_f32 v[214:215], v[214:215], v[236:237] op_sel_hi:[1,0] neg_lo:[0,1] neg_hi:[0,1]
	v_pk_add_f32 v[216:217], v[216:217], v[236:237] op_sel_hi:[1,0] neg_lo:[0,1] neg_hi:[0,1]
	v_pk_add_f32 v[218:219], v[218:219], v[236:237] op_sel_hi:[1,0] neg_lo:[0,1] neg_hi:[0,1]
	v_pk_add_f32 v[220:221], v[220:221], v[236:237] op_sel_hi:[1,0] neg_lo:[0,1] neg_hi:[0,1]
	v_pk_add_f32 v[222:223], v[222:223], v[236:237] op_sel_hi:[1,0] neg_lo:[0,1] neg_hi:[0,1]
	v_pk_add_f32 v[224:225], v[224:225], v[236:237] op_sel_hi:[1,0] neg_lo:[0,1] neg_hi:[0,1]
	v_mul_f32_e32 v193, v193, v238
	v_pk_mul_f32 v[68:69], v[68:69], v[238:239] op_sel_hi:[1,0]
	v_pk_mul_f32 v[70:71], v[70:71], v[238:239] op_sel_hi:[1,0]
	v_pk_mul_f32 v[72:73], v[72:73], v[238:239] op_sel_hi:[1,0]
	v_pk_mul_f32 v[74:75], v[74:75], v[238:239] op_sel_hi:[1,0]
	v_pk_mul_f32 v[76:77], v[76:77], v[238:239] op_sel_hi:[1,0]
	v_pk_mul_f32 v[78:79], v[78:79], v[238:239] op_sel_hi:[1,0]
	v_pk_mul_f32 v[80:81], v[80:81], v[238:239] op_sel_hi:[1,0]
	v_pk_mul_f32 v[82:83], v[82:83], v[238:239] op_sel_hi:[1,0]
	v_pk_mul_f32 v[52:53], v[52:53], v[238:239] op_sel_hi:[1,0]
	v_pk_mul_f32 v[54:55], v[54:55], v[238:239] op_sel_hi:[1,0]
	v_pk_mul_f32 v[56:57], v[56:57], v[238:239] op_sel_hi:[1,0]
	v_pk_mul_f32 v[58:59], v[58:59], v[238:239] op_sel_hi:[1,0]
	v_pk_mul_f32 v[60:61], v[60:61], v[238:239] op_sel_hi:[1,0]
	v_pk_mul_f32 v[62:63], v[62:63], v[238:239] op_sel_hi:[1,0]
	v_pk_mul_f32 v[64:65], v[64:65], v[238:239] op_sel_hi:[1,0]
	v_pk_mul_f32 v[66:67], v[66:67], v[238:239] op_sel_hi:[1,0]
	v_pk_mul_f32 v[36:37], v[36:37], v[238:239] op_sel_hi:[1,0]
	v_pk_mul_f32 v[38:39], v[38:39], v[238:239] op_sel_hi:[1,0]
	v_pk_mul_f32 v[40:41], v[40:41], v[238:239] op_sel_hi:[1,0]
	v_pk_mul_f32 v[42:43], v[42:43], v[238:239] op_sel_hi:[1,0]
	v_pk_mul_f32 v[44:45], v[44:45], v[238:239] op_sel_hi:[1,0]
	v_pk_mul_f32 v[46:47], v[46:47], v[238:239] op_sel_hi:[1,0]
	v_pk_mul_f32 v[48:49], v[48:49], v[238:239] op_sel_hi:[1,0]
	v_pk_mul_f32 v[50:51], v[50:51], v[238:239] op_sel_hi:[1,0]
	v_pk_mul_f32 v[20:21], v[20:21], v[238:239] op_sel_hi:[1,0]
	v_pk_mul_f32 v[22:23], v[22:23], v[238:239] op_sel_hi:[1,0]
	v_pk_mul_f32 v[24:25], v[24:25], v[238:239] op_sel_hi:[1,0]
	v_pk_mul_f32 v[26:27], v[26:27], v[238:239] op_sel_hi:[1,0]
	v_pk_mul_f32 v[28:29], v[28:29], v[238:239] op_sel_hi:[1,0]
	v_pk_mul_f32 v[30:31], v[30:31], v[238:239] op_sel_hi:[1,0]
	v_pk_mul_f32 v[32:33], v[32:33], v[238:239] op_sel_hi:[1,0]
	v_pk_mul_f32 v[34:35], v[34:35], v[238:239] op_sel_hi:[1,0]
	v_add_f32_e32 v192, v192, v236
	ds_read_b64_tr_b16 v[10:11], v197 offset:25600
	ds_read_b64_tr_b16 v[12:13], v197 offset:28160
	ds_read_b64_tr_b16 v[14:15], v197 offset:25664
	ds_read_b64_tr_b16 v[16:17], v197 offset:28224
	ds_read_b64_tr_b16 v[202:203], v197 offset:25728
	ds_read_b64_tr_b16 v[204:205], v197 offset:28288
	ds_read_b64_tr_b16 v[206:207], v197 offset:25792
	ds_read_b64_tr_b16 v[208:209], v197 offset:28352
	v_exp_f32_e32 v100, v100
	v_exp_f32_e32 v101, v101
	v_exp_f32_e32 v102, v102
	v_exp_f32_e32 v103, v103
	v_exp_f32_e32 v104, v104
	v_exp_f32_e32 v105, v105
	v_exp_f32_e32 v106, v106
	v_exp_f32_e32 v107, v107
	v_exp_f32_e32 v108, v108
	v_exp_f32_e32 v109, v109
	v_exp_f32_e32 v110, v110
	v_exp_f32_e32 v111, v111
	v_exp_f32_e32 v112, v112
	v_exp_f32_e32 v113, v113
	v_exp_f32_e32 v114, v114
	v_exp_f32_e32 v115, v115
	v_exp_f32_e32 v84, v84
	v_exp_f32_e32 v85, v85
	v_exp_f32_e32 v86, v86
	v_exp_f32_e32 v87, v87
	v_exp_f32_e32 v88, v88
	v_exp_f32_e32 v89, v89
	v_exp_f32_e32 v90, v90
	v_exp_f32_e32 v91, v91
	v_exp_f32_e32 v92, v92
	v_exp_f32_e32 v93, v93
	v_exp_f32_e32 v94, v94
	v_exp_f32_e32 v95, v95
	v_exp_f32_e32 v96, v96
	v_exp_f32_e32 v97, v97
	v_exp_f32_e32 v98, v98
	v_exp_f32_e32 v99, v99
	v_add_f32_e32 v234, 0, v100
	v_add_f32_e32 v234, v101, v234
	v_add_f32_e32 v234, v102, v234
	v_add_f32_e32 v234, v103, v234
	v_add_f32_e32 v234, v104, v234
	v_add_f32_e32 v234, v105, v234
	v_add_f32_e32 v234, v106, v234
	v_add_f32_e32 v234, v107, v234
	v_add_f32_e32 v234, v108, v234
	v_add_f32_e32 v234, v109, v234
	v_add_f32_e32 v234, v110, v234
	v_add_f32_e32 v234, v111, v234
	v_add_f32_e32 v234, v112, v234
	v_add_f32_e32 v234, v113, v234
	v_add_f32_e32 v234, v114, v234
	v_add_f32_e32 v234, v115, v234
	v_add_f32_e32 v234, v84, v234
	v_add_f32_e32 v234, v85, v234
	v_add_f32_e32 v234, v86, v234
	v_add_f32_e32 v234, v87, v234
	v_add_f32_e32 v234, v88, v234
	v_add_f32_e32 v234, v89, v234
	v_add_f32_e32 v234, v90, v234
	v_add_f32_e32 v234, v91, v234
	v_add_f32_e32 v234, v92, v234
	v_add_f32_e32 v234, v93, v234
	v_add_f32_e32 v234, v94, v234
	v_add_f32_e32 v234, v95, v234
	v_add_f32_e32 v234, v96, v234
	v_add_f32_e32 v234, v97, v234
	v_add_f32_e32 v234, v98, v234
	v_add_f32_e32 v234, v99, v234
	s_branch .Lm_post
